# GEMM pipeline (re)start: all 7 half-tile stages issued before the first wait (one load round trip instead of two)
# baseline (speedup 1.0000x reference)
.LBB0_232:
	s_add_i32 s6, s20, 0
	s_add_i32 m0, s6, 0x10000
	s_nop 0
	global_load_lds_dwordx4 v192, s[60:61]
	s_add_i32 m0, s6, 0x12000
	s_add_u32 s4, s60, s44
	global_load_lds_dwordx4 v190, s[60:61]
	s_addc_u32 s5, s61, s45
	s_add_i32 m0, s6, 0x14000
	s_nop 0
	global_load_lds_dwordx4 v192, s[4:5]
	s_add_i32 m0, s6, 0x16000
	s_nop 0
	global_load_lds_dwordx4 v190, s[4:5]
	s_mov_b32 m0, s6
	s_nop 0
	global_load_lds_dwordx4 v188, s[54:55]
	s_add_i32 m0, s6, 0x2000
	s_add_u32 s8, s54, s44
	global_load_lds_dwordx4 v186, s[54:55]
	s_addc_u32 s9, s55, s45
	s_add_i32 m0, s6, 0x4000
	s_nop 0
	global_load_lds_dwordx4 v188, s[8:9]
	s_add_i32 m0, s6, 0x6000
	s_nop 0
	global_load_lds_dwordx4 v186, s[8:9]
	v_mov_b32_e32 v193, v113
	v_lshl_add_u64 v[130:131], s[60:61], 0, v[192:193]
	v_mov_b32_e32 v191, v113
	v_lshl_add_u64 v[132:133], s[60:61], 0, v[190:191]
	v_mov_b32_e32 v189, v113
	v_lshl_add_u64 v[130:131], v[130:131], 0, s[42:43]
	s_add_i32 m0, s6, 0x18000
	v_lshl_add_u64 v[138:139], s[54:55], 0, v[188:189]
	v_mov_b32_e32 v187, v113
	global_load_lds_dwordx4 v[130:131], off
	v_lshl_add_u64 v[130:131], v[132:133], 0, s[42:43]
	s_add_i32 m0, s6, 0x1a000
	v_lshl_add_u64 v[140:141], s[54:55], 0, v[186:187]
	global_load_lds_dwordx4 v[130:131], off
	v_lshl_add_u64 v[130:131], v[138:139], 0, s[42:43]
	s_add_i32 m0, s6, 0x8000
	v_lshl_add_u64 v[134:135], s[4:5], 0, v[192:193]
	global_load_lds_dwordx4 v[130:131], off
	v_lshl_add_u64 v[130:131], v[140:141], 0, s[42:43]
	s_add_i32 m0, s6, 0xa000
	v_lshl_add_u64 v[136:137], s[4:5], 0, v[190:191]
	global_load_lds_dwordx4 v[130:131], off
	v_lshl_add_u64 v[130:131], v[134:135], 0, s[42:43]
	s_add_i32 m0, s6, 0x1c000
	s_nop 0
	global_load_lds_dwordx4 v[130:131], off
	v_lshl_add_u64 v[130:131], v[136:137], 0, s[42:43]
	s_add_i32 m0, s6, 0x1e000
	s_nop 0
	global_load_lds_dwordx4 v[130:131], off
	v_readlane_b32 s8, v254, 56
	v_readlane_b32 s9, v254, 57
	s_andn2_b64 vcc, exec, s[8:9]
	s_cbranch_vccnz .LBB0_234
	s_barrier
.LBB0_234:
	s_waitcnt vmcnt(8)
	s_barrier
	s_waitcnt vmcnt(6)
	s_barrier
